# HGRN2 sample pair body rewritten by hand (32 k rows x 2 v columns per lane, packed f32, batched LDS broadcasts); P2b conv pairs 2,2,2,1,1,1,0,0
# speedup vs baseline: 1.0114x; 1.0056x over previous
; __device__ __forceinline__ float bf2f(bf16_t b) { return __uint_as_float(((unsigned)b) << 16); }
; #define LDS_BARRIER() do { asm volatile("s_waitcnt lgkmcnt(0)" ::: "memory"); __builtin_amdgcn_s_barrier(); asm volatile("" ::: "memory"); } while (0)
; __device__ __forceinline__ void hgrn_sample_pair(const Params& p, float* lds, int unit) {
;     int tid = threadIdx.x; asm volatile("" : "+v"(tid));
;     const int half = tid >> 8, v = tid & 127, kg = (tid >> 7) & 1, lane = tid & 63, wq = (tid >> 6) & 3;
;     unsigned char* ws = p.ws;
;     const bf16_t* Q = (const bf16_t*)(ws + WS_Q); const bf16_t* Kk = (const bf16_t*)(ws + WS_K); const bf16_t* V = (const bf16_t*)(ws + WS_V); const bf16_t* Gt = (const bf16_t*)(ws + WS_G);
;     const float* LOGF = (const float*)(ws + WS_LOGF); bf16_t* CAT = (bf16_t*)(ws + WS_CAT);
;     const int n = unit >> 2, h = unit & 3, rowbase = MP + n * DS;
;     float* sq = lds + half * 3072; float* sk = sq + 512; float* sf = sq + 1024; float* sv = sq + 1536; float* po = sq + 2048;
;     float S[64]; float gn0 = 0.f, gn1 = 0.f, gt0 = 0.f, gt1 = 0.f;
;     if (unit >= 0) {
;         { const size_t g = (size_t)(rowbase + wq) * 512 + h * 128; gn0 = p.in[I_HON][lane]; gn1 = p.in[I_HON][lane + 64]; gt0 = bf2f(Gt[g + lane]); gt1 = bf2f(Gt[g + lane + 64]); }
;         const float* s0 = p.in[I_SH] + ((size_t)(n * HEADS + h) * DK) * DV + (size_t)(64 * kg) * DV + v;
; #pragma unroll
;         for (int k = 0; k < 64; ++k) S[k] = __builtin_nontemporal_load(s0 + (size_t)k * DV);
; #pragma unroll
;         for (int i = 0; i < 2; ++i) { const int idx = (tid & 255) + 256 * i, t = idx >> 7, c = idx & 127; const size_t g = (size_t)(rowbase + t) * 512 + h * 128 + c;
;             sq[idx] = bf2f(Q[g]); sk[idx] = bf2f(Kk[g]); sf[idx] = __builtin_amdgcn_exp2f(LOGF[g]); sv[idx] = bf2f(V[g]); }
;     }
;     LDS_BARRIER();
.LBB0_327:
	s_mov_b64 s[10:11], exec
	s_waitcnt vmcnt(16)
	v_readfirstlane_b32 s4, v0
	v_readfirstlane_b32 s5, v176
	s_lshr_b32 s20, s5, 8
	s_lshr_b32 s5, s5, 6
	s_and_b32 s5, s5, 3
	s_lshr_b32 s21, s4, 2
	s_and_b32 s4, s4, 3
	s_lshl_b32 s36, s21, 2
	s_add_u32 s36, s36, s4
	s_lshl_b32 s36, s36, 16
	s_lshl_b32 s37, s5, 14
	s_add_u32 s51, s36, s37
	v_readlane_b32 s36, v247, 8
	v_readlane_b32 s37, v247, 9
	v_readlane_b32 s38, v247, 30
	v_readlane_b32 s39, v247, 31
	s_add_u32 s36, s36, s51
	s_addc_u32 s37, s37, 0
	s_add_u32 s38, s38, s51
	s_addc_u32 s39, s39, 0
	s_add_u32 s38, s38, 0x4478000
	s_addc_u32 s39, s39, 0
	s_lshl_b32 s21, s21, 2
	s_addk_i32 s21, 0x4000
	s_lshl_b32 s50, s21, 10
	s_lshl_b32 s51, s4, 8
	s_add_u32 s50, s50, s51
	v_readlane_b32 s48, v247, 38
	v_readlane_b32 s49, v247, 39
	s_add_u32 s40, s48, s50
	s_addc_u32 s41, s49, 0
	s_add_u32 s40, s40, 0x2375e00
	s_addc_u32 s41, s41, 0
	s_add_u32 s42, s48, s50
	s_addc_u32 s43, s49, 0
	s_add_u32 s42, s42, 0x33f5e00
	s_addc_u32 s43, s43, 0
	s_add_u32 s44, s48, s50
	s_addc_u32 s45, s49, 0
	s_add_u32 s44, s44, 0x4475e00
	s_addc_u32 s45, s45, 0
	s_add_u32 s46, s48, s50
	s_addc_u32 s47, s49, 0
	s_add_u32 s46, s46, 0x54f5e00
	s_addc_u32 s47, s47, 0
	s_lshl_b32 s50, s50, 1
	s_add_u32 s48, s48, s50
	s_addc_u32 s49, s49, 0
	s_add_u32 s48, s48, 0x75f5e00
	s_addc_u32 s49, s49, 0
	s_add_u32 s50, s48, 0x1000
	s_addc_u32 s51, s49, 0
	s_lshl_b32 s99, s5, 10
	s_add_u32 s46, s46, s99
	s_addc_u32 s47, s47, 0
	v_lshlrev_b32_e32 v207, 3, v206
	v_lshlrev_b32_e32 v237, 2, v206
	v_lshlrev_b32_e32 v238, 1, v206
	v_and_b32_e32 v230, 0xff, v176
	s_lshl_b32 s99, s20, 14
	v_lshl_add_u32 v232, v230, 2, s99
	v_lshlrev_b32_e32 v231, 2, v230
	v_lshrrev_b32_e32 v25, 7, v230
	v_mul_u32_u24_e32 v25, 0x180, v25
	v_add_u32_e32 v230, v230, v25
	v_lshlrev_b32_e32 v231, 2, v230
	v_lshlrev_b32_e32 v230, 1, v230
	global_load_dword v21, v237, s[70:71]
	global_load_dword v22, v237, s[70:71] offset:256
	global_load_ushort v23, v238, s[46:47]
	global_load_ushort v24, v238, s[46:47] offset:128
	global_load_ushort v239, v230, s[40:41]
	global_load_ushort v240, v230, s[40:41] offset:2048
	global_load_ushort v241, v230, s[42:43]
	global_load_ushort v242, v230, s[42:43] offset:2048
	global_load_ushort v243, v230, s[44:45]
	global_load_ushort v244, v230, s[44:45] offset:2048
	global_load_dword v245, v231, s[48:49]
	global_load_dword v246, v231, s[50:51]
	global_load_dwordx2 v[100:101], v207, s[36:37] nt
	global_load_dwordx2 v[102:103], v207, s[36:37] offset:512 nt
	global_load_dwordx2 v[104:105], v207, s[36:37] offset:1024 nt
	global_load_dwordx2 v[106:107], v207, s[36:37] offset:1536 nt
	global_load_dwordx2 v[108:109], v207, s[36:37] offset:2048 nt
	global_load_dwordx2 v[110:111], v207, s[36:37] offset:2560 nt
	global_load_dwordx2 v[112:113], v207, s[36:37] offset:3072 nt
	global_load_dwordx2 v[114:115], v207, s[36:37] offset:3584 nt
	s_add_u32 s36, s36, 0x1000
	s_addc_u32 s37, s37, 0
	global_load_dwordx2 v[116:117], v207, s[36:37] nt
	global_load_dwordx2 v[118:119], v207, s[36:37] offset:512 nt
	global_load_dwordx2 v[120:121], v207, s[36:37] offset:1024 nt
	global_load_dwordx2 v[122:123], v207, s[36:37] offset:1536 nt
	global_load_dwordx2 v[124:125], v207, s[36:37] offset:2048 nt
	global_load_dwordx2 v[126:127], v207, s[36:37] offset:2560 nt
	global_load_dwordx2 v[128:129], v207, s[36:37] offset:3072 nt
	global_load_dwordx2 v[130:131], v207, s[36:37] offset:3584 nt
	s_add_u32 s36, s36, 0x1000
	s_addc_u32 s37, s37, 0
	global_load_dwordx2 v[132:133], v207, s[36:37] nt
	global_load_dwordx2 v[134:135], v207, s[36:37] offset:512 nt
	global_load_dwordx2 v[136:137], v207, s[36:37] offset:1024 nt
	global_load_dwordx2 v[138:139], v207, s[36:37] offset:1536 nt
	global_load_dwordx2 v[140:141], v207, s[36:37] offset:2048 nt
	global_load_dwordx2 v[142:143], v207, s[36:37] offset:2560 nt
	global_load_dwordx2 v[144:145], v207, s[36:37] offset:3072 nt
	global_load_dwordx2 v[146:147], v207, s[36:37] offset:3584 nt
	s_add_u32 s36, s36, 0x1000
	s_addc_u32 s37, s37, 0
	global_load_dwordx2 v[148:149], v207, s[36:37] nt
	global_load_dwordx2 v[150:151], v207, s[36:37] offset:512 nt
	global_load_dwordx2 v[152:153], v207, s[36:37] offset:1024 nt
	global_load_dwordx2 v[154:155], v207, s[36:37] offset:1536 nt
	global_load_dwordx2 v[156:157], v207, s[36:37] offset:2048 nt
	global_load_dwordx2 v[158:159], v207, s[36:37] offset:2560 nt
	global_load_dwordx2 v[160:161], v207, s[36:37] offset:3072 nt
	global_load_dwordx2 v[162:163], v207, s[36:37] offset:3584 nt
	s_lshl_b32 s4, s5, 7
	s_add_u32 s4, s4, s99
	v_mov_b32_e32 v233, s4
	v_lshl_add_u32 v234, v206, 3, s99
	s_lshl_b32 s4, s5, 9
	s_add_u32 s4, s4, s99
	v_lshl_add_u32 v235, v206, 3, s4
	s_lshl_b32 s4, s5, 11
	s_add_u32 s4, s4, s99
	v_lshl_add_u32 v236, v206, 2, s4
	v_readlane_b32 s20, v247, 38
	v_readlane_b32 s21, v247, 39
	s_waitcnt vmcnt(32)
	v_lshlrev_b32_e32 v239, 16, v239
	v_lshlrev_b32_e32 v240, 16, v240
	v_lshlrev_b32_e32 v241, 16, v241
	v_lshlrev_b32_e32 v242, 16, v242
	v_lshlrev_b32_e32 v243, 16, v243
	v_lshlrev_b32_e32 v244, 16, v244
	v_exp_f32_e32 v245, v245
	v_exp_f32_e32 v246, v246
	ds_write_b32 v232, v239
	ds_write_b32 v232, v240 offset:1024
	ds_write_b32 v232, v241 offset:2048
	ds_write_b32 v232, v242 offset:3072
	ds_write_b32 v232, v243 offset:6144
	ds_write_b32 v232, v244 offset:7168
	ds_write_b32 v232, v245 offset:4096
	ds_write_b32 v232, v246 offset:5120
	v_lshlrev_b32_e32 v23, 16, v23
	v_lshlrev_b32_e32 v24, 16, v24
	s_waitcnt lgkmcnt(0)
	s_barrier
; __device__ __forceinline__ void hgrn_sample_pair(const Params& p, float* lds, int unit) {
;     ...
;         for (int t = 0; t < DS; ++t) { const float vt = sv[t * 128 + v]; float o = 0.f; const float* f_ = sf + t * 128 + 64 * kg; const float* k_ = sk + t * 128 + 64 * kg; const float* q_ = sq + t * 128 + 64 * kg;
; #pragma unroll
;             for (int k = 0; k < 64; ++k) { S[k] = f_[k] * S[k] + k_[k] * vt; o += q_[k] * S[k]; }
;             po[(t * 2 + kg) * 128 + v] = o; }
	ds_read_b64 v[204:205], v234 offset:6144
	ds_read_b128 v[164:167], v233 offset:4096
	ds_read_b128 v[168:171], v233 offset:4112
	ds_read_b128 v[172:175], v233 offset:2048
	ds_read_b128 v[180:183], v233 offset:2064
	ds_read_b128 v[184:187], v233 offset:0
	ds_read_b128 v[188:191], v233 offset:16
	ds_read_b128 v[192:195], v233 offset:4128
	ds_read_b128 v[196:199], v233 offset:4144
	ds_read_b128 v[200:203], v233 offset:2080
	ds_read_b128 v[208:211], v233 offset:2096
	ds_read_b128 v[212:215], v233 offset:32
	ds_read_b128 v[216:219], v233 offset:48
	s_waitcnt lgkmcnt(6)
	s_waitcnt vmcnt(31)
	v_pk_mul_f32 v[222:223], v[204:205], v[172:173] op_sel:[0,0] op_sel_hi:[1,0]
	v_pk_fma_f32 v[100:101], v[100:101], v[164:165], v[222:223] op_sel:[0,0,0] op_sel_hi:[1,0,1]
	v_pk_mul_f32 v[226:227], v[100:101], v[184:185] op_sel:[0,0] op_sel_hi:[1,0]
	s_waitcnt vmcnt(30)
	v_pk_mul_f32 v[224:225], v[204:205], v[172:173] op_sel:[0,1] op_sel_hi:[1,1]
	v_pk_fma_f32 v[102:103], v[102:103], v[164:165], v[224:225] op_sel:[0,1,0] op_sel_hi:[1,1,1]
	v_pk_mul_f32 v[228:229], v[102:103], v[184:185] op_sel:[0,1] op_sel_hi:[1,1]
	s_waitcnt vmcnt(29)
	v_pk_mul_f32 v[222:223], v[204:205], v[174:175] op_sel:[0,0] op_sel_hi:[1,0]
	v_pk_fma_f32 v[104:105], v[104:105], v[166:167], v[222:223] op_sel:[0,0,0] op_sel_hi:[1,0,1]
	v_pk_fma_f32 v[226:227], v[104:105], v[186:187], v[226:227] op_sel:[0,0,0] op_sel_hi:[1,0,1]
	s_waitcnt vmcnt(28)
	v_pk_mul_f32 v[224:225], v[204:205], v[174:175] op_sel:[0,1] op_sel_hi:[1,1]
	v_pk_fma_f32 v[106:107], v[106:107], v[166:167], v[224:225] op_sel:[0,1,0] op_sel_hi:[1,1,1]
	v_pk_fma_f32 v[228:229], v[106:107], v[186:187], v[228:229] op_sel:[0,1,0] op_sel_hi:[1,1,1]
	s_waitcnt vmcnt(27)
	v_pk_mul_f32 v[222:223], v[204:205], v[180:181] op_sel:[0,0] op_sel_hi:[1,0]
	v_pk_fma_f32 v[108:109], v[108:109], v[168:169], v[222:223] op_sel:[0,0,0] op_sel_hi:[1,0,1]
	v_pk_fma_f32 v[226:227], v[108:109], v[188:189], v[226:227] op_sel:[0,0,0] op_sel_hi:[1,0,1]
	s_waitcnt vmcnt(26)
	v_pk_mul_f32 v[224:225], v[204:205], v[180:181] op_sel:[0,1] op_sel_hi:[1,1]
	v_pk_fma_f32 v[110:111], v[110:111], v[168:169], v[224:225] op_sel:[0,1,0] op_sel_hi:[1,1,1]
	v_pk_fma_f32 v[228:229], v[110:111], v[188:189], v[228:229] op_sel:[0,1,0] op_sel_hi:[1,1,1]
	s_waitcnt vmcnt(25)
	v_pk_mul_f32 v[222:223], v[204:205], v[182:183] op_sel:[0,0] op_sel_hi:[1,0]
	v_pk_fma_f32 v[112:113], v[112:113], v[170:171], v[222:223] op_sel:[0,0,0] op_sel_hi:[1,0,1]
	v_pk_fma_f32 v[226:227], v[112:113], v[190:191], v[226:227] op_sel:[0,0,0] op_sel_hi:[1,0,1]
	s_waitcnt vmcnt(24)
	v_pk_mul_f32 v[224:225], v[204:205], v[182:183] op_sel:[0,1] op_sel_hi:[1,1]
	v_pk_fma_f32 v[114:115], v[114:115], v[170:171], v[224:225] op_sel:[0,1,0] op_sel_hi:[1,1,1]
	v_pk_fma_f32 v[228:229], v[114:115], v[190:191], v[228:229] op_sel:[0,1,0] op_sel_hi:[1,1,1]
	ds_read_b128 v[164:167], v233 offset:4160
	ds_read_b128 v[168:171], v233 offset:4176
	ds_read_b128 v[172:175], v233 offset:2112
	ds_read_b128 v[180:183], v233 offset:2128
	ds_read_b128 v[184:187], v233 offset:64
	ds_read_b128 v[188:191], v233 offset:80
	s_waitcnt lgkmcnt(6)
	s_waitcnt vmcnt(23)
	v_pk_mul_f32 v[222:223], v[204:205], v[200:201] op_sel:[0,0] op_sel_hi:[1,0]
	v_pk_fma_f32 v[116:117], v[116:117], v[192:193], v[222:223] op_sel:[0,0,0] op_sel_hi:[1,0,1]
	v_pk_fma_f32 v[226:227], v[116:117], v[212:213], v[226:227] op_sel:[0,0,0] op_sel_hi:[1,0,1]
	s_waitcnt vmcnt(22)
	v_pk_mul_f32 v[224:225], v[204:205], v[200:201] op_sel:[0,1] op_sel_hi:[1,1]
	v_pk_fma_f32 v[118:119], v[118:119], v[192:193], v[224:225] op_sel:[0,1,0] op_sel_hi:[1,1,1]
	v_pk_fma_f32 v[228:229], v[118:119], v[212:213], v[228:229] op_sel:[0,1,0] op_sel_hi:[1,1,1]
	s_waitcnt vmcnt(21)
	v_pk_mul_f32 v[222:223], v[204:205], v[202:203] op_sel:[0,0] op_sel_hi:[1,0]
	v_pk_fma_f32 v[120:121], v[120:121], v[194:195], v[222:223] op_sel:[0,0,0] op_sel_hi:[1,0,1]
	v_pk_fma_f32 v[226:227], v[120:121], v[214:215], v[226:227] op_sel:[0,0,0] op_sel_hi:[1,0,1]
	s_waitcnt vmcnt(20)
	v_pk_mul_f32 v[224:225], v[204:205], v[202:203] op_sel:[0,1] op_sel_hi:[1,1]
	v_pk_fma_f32 v[122:123], v[122:123], v[194:195], v[224:225] op_sel:[0,1,0] op_sel_hi:[1,1,1]
	v_pk_fma_f32 v[228:229], v[122:123], v[214:215], v[228:229] op_sel:[0,1,0] op_sel_hi:[1,1,1]
	s_waitcnt vmcnt(19)
	v_pk_mul_f32 v[222:223], v[204:205], v[208:209] op_sel:[0,0] op_sel_hi:[1,0]
	v_pk_fma_f32 v[124:125], v[124:125], v[196:197], v[222:223] op_sel:[0,0,0] op_sel_hi:[1,0,1]
	v_pk_fma_f32 v[226:227], v[124:125], v[216:217], v[226:227] op_sel:[0,0,0] op_sel_hi:[1,0,1]
	s_waitcnt vmcnt(18)
	v_pk_mul_f32 v[224:225], v[204:205], v[208:209] op_sel:[0,1] op_sel_hi:[1,1]
	v_pk_fma_f32 v[126:127], v[126:127], v[196:197], v[224:225] op_sel:[0,1,0] op_sel_hi:[1,1,1]
	v_pk_fma_f32 v[228:229], v[126:127], v[216:217], v[228:229] op_sel:[0,1,0] op_sel_hi:[1,1,1]
	s_waitcnt vmcnt(17)
	v_pk_mul_f32 v[222:223], v[204:205], v[210:211] op_sel:[0,0] op_sel_hi:[1,0]
	v_pk_fma_f32 v[128:129], v[128:129], v[198:199], v[222:223] op_sel:[0,0,0] op_sel_hi:[1,0,1]
	v_pk_fma_f32 v[226:227], v[128:129], v[218:219], v[226:227] op_sel:[0,0,0] op_sel_hi:[1,0,1]
	s_waitcnt vmcnt(16)
	v_pk_mul_f32 v[224:225], v[204:205], v[210:211] op_sel:[0,1] op_sel_hi:[1,1]
	v_pk_fma_f32 v[130:131], v[130:131], v[198:199], v[224:225] op_sel:[0,1,0] op_sel_hi:[1,1,1]
	v_pk_fma_f32 v[228:229], v[130:131], v[218:219], v[228:229] op_sel:[0,1,0] op_sel_hi:[1,1,1]
	ds_read_b128 v[192:195], v233 offset:4192
	ds_read_b128 v[196:199], v233 offset:4208
	ds_read_b128 v[200:203], v233 offset:2144
	ds_read_b128 v[208:211], v233 offset:2160
	ds_read_b128 v[212:215], v233 offset:96
	ds_read_b128 v[216:219], v233 offset:112
	s_waitcnt lgkmcnt(6)
; __device__ __forceinline__ void hgrn_sample_pair(const Params& p, float* lds, int unit) {
;     ...
;         for (int t = 0; t < DS; ++t) { const float vt = sv[t * 128 + v]; float o = 0.f; const float* f_ = sf + t * 128 + 64 * kg; const float* k_ = sk + t * 128 + 64 * kg; const float* q_ = sq + t * 128 + 64 * kg;
; #pragma unroll
;             for (int k = 0; k < 64; ++k) { S[k] = f_[k] * S[k] + k_[k] * vt; o += q_[k] * S[k]; }
;             po[(t * 2 + kg) * 128 + v] = o; }
	s_waitcnt vmcnt(15)
	v_pk_mul_f32 v[222:223], v[204:205], v[172:173] op_sel:[0,0] op_sel_hi:[1,0]
	v_pk_fma_f32 v[132:133], v[132:133], v[164:165], v[222:223] op_sel:[0,0,0] op_sel_hi:[1,0,1]
	v_pk_fma_f32 v[226:227], v[132:133], v[184:185], v[226:227] op_sel:[0,0,0] op_sel_hi:[1,0,1]
	s_waitcnt vmcnt(14)
	v_pk_mul_f32 v[224:225], v[204:205], v[172:173] op_sel:[0,1] op_sel_hi:[1,1]
	v_pk_fma_f32 v[134:135], v[134:135], v[164:165], v[224:225] op_sel:[0,1,0] op_sel_hi:[1,1,1]
	v_pk_fma_f32 v[228:229], v[134:135], v[184:185], v[228:229] op_sel:[0,1,0] op_sel_hi:[1,1,1]
	s_waitcnt vmcnt(13)
	v_pk_mul_f32 v[222:223], v[204:205], v[174:175] op_sel:[0,0] op_sel_hi:[1,0]
	v_pk_fma_f32 v[136:137], v[136:137], v[166:167], v[222:223] op_sel:[0,0,0] op_sel_hi:[1,0,1]
	v_pk_fma_f32 v[226:227], v[136:137], v[186:187], v[226:227] op_sel:[0,0,0] op_sel_hi:[1,0,1]
	s_waitcnt vmcnt(12)
	v_pk_mul_f32 v[224:225], v[204:205], v[174:175] op_sel:[0,1] op_sel_hi:[1,1]
	v_pk_fma_f32 v[138:139], v[138:139], v[166:167], v[224:225] op_sel:[0,1,0] op_sel_hi:[1,1,1]
	v_pk_fma_f32 v[228:229], v[138:139], v[186:187], v[228:229] op_sel:[0,1,0] op_sel_hi:[1,1,1]
	s_waitcnt vmcnt(11)
	v_pk_mul_f32 v[222:223], v[204:205], v[180:181] op_sel:[0,0] op_sel_hi:[1,0]
	v_pk_fma_f32 v[140:141], v[140:141], v[168:169], v[222:223] op_sel:[0,0,0] op_sel_hi:[1,0,1]
	v_pk_fma_f32 v[226:227], v[140:141], v[188:189], v[226:227] op_sel:[0,0,0] op_sel_hi:[1,0,1]
	s_waitcnt vmcnt(10)
	v_pk_mul_f32 v[224:225], v[204:205], v[180:181] op_sel:[0,1] op_sel_hi:[1,1]
	v_pk_fma_f32 v[142:143], v[142:143], v[168:169], v[224:225] op_sel:[0,1,0] op_sel_hi:[1,1,1]
	v_pk_fma_f32 v[228:229], v[142:143], v[188:189], v[228:229] op_sel:[0,1,0] op_sel_hi:[1,1,1]
	s_waitcnt vmcnt(9)
	v_pk_mul_f32 v[222:223], v[204:205], v[182:183] op_sel:[0,0] op_sel_hi:[1,0]
	v_pk_fma_f32 v[144:145], v[144:145], v[170:171], v[222:223] op_sel:[0,0,0] op_sel_hi:[1,0,1]
	v_pk_fma_f32 v[226:227], v[144:145], v[190:191], v[226:227] op_sel:[0,0,0] op_sel_hi:[1,0,1]
	s_waitcnt vmcnt(8)
	v_pk_mul_f32 v[224:225], v[204:205], v[182:183] op_sel:[0,1] op_sel_hi:[1,1]
	v_pk_fma_f32 v[146:147], v[146:147], v[170:171], v[224:225] op_sel:[0,1,0] op_sel_hi:[1,1,1]
	v_pk_fma_f32 v[228:229], v[146:147], v[190:191], v[228:229] op_sel:[0,1,0] op_sel_hi:[1,1,1]
	ds_read_b64 v[220:221], v234 offset:6656
	ds_read_b128 v[164:167], v233 offset:4608
	ds_read_b128 v[168:171], v233 offset:4624
	ds_read_b128 v[172:175], v233 offset:2560
	ds_read_b128 v[180:183], v233 offset:2576
	ds_read_b128 v[184:187], v233 offset:512
	ds_read_b128 v[188:191], v233 offset:528
	s_waitcnt lgkmcnt(7)
	s_waitcnt vmcnt(7)
	v_pk_mul_f32 v[222:223], v[204:205], v[200:201] op_sel:[0,0] op_sel_hi:[1,0]
	v_pk_fma_f32 v[148:149], v[148:149], v[192:193], v[222:223] op_sel:[0,0,0] op_sel_hi:[1,0,1]
	v_pk_fma_f32 v[226:227], v[148:149], v[212:213], v[226:227] op_sel:[0,0,0] op_sel_hi:[1,0,1]
	s_waitcnt vmcnt(6)
	v_pk_mul_f32 v[224:225], v[204:205], v[200:201] op_sel:[0,1] op_sel_hi:[1,1]
	v_pk_fma_f32 v[150:151], v[150:151], v[192:193], v[224:225] op_sel:[0,1,0] op_sel_hi:[1,1,1]
	v_pk_fma_f32 v[228:229], v[150:151], v[212:213], v[228:229] op_sel:[0,1,0] op_sel_hi:[1,1,1]
	s_waitcnt vmcnt(5)
	v_pk_mul_f32 v[222:223], v[204:205], v[202:203] op_sel:[0,0] op_sel_hi:[1,0]
	v_pk_fma_f32 v[152:153], v[152:153], v[194:195], v[222:223] op_sel:[0,0,0] op_sel_hi:[1,0,1]
	v_pk_fma_f32 v[226:227], v[152:153], v[214:215], v[226:227] op_sel:[0,0,0] op_sel_hi:[1,0,1]
	s_waitcnt vmcnt(4)
	v_pk_mul_f32 v[224:225], v[204:205], v[202:203] op_sel:[0,1] op_sel_hi:[1,1]
	v_pk_fma_f32 v[154:155], v[154:155], v[194:195], v[224:225] op_sel:[0,1,0] op_sel_hi:[1,1,1]
	v_pk_fma_f32 v[228:229], v[154:155], v[214:215], v[228:229] op_sel:[0,1,0] op_sel_hi:[1,1,1]
	s_waitcnt vmcnt(3)
	v_pk_mul_f32 v[222:223], v[204:205], v[208:209] op_sel:[0,0] op_sel_hi:[1,0]
	v_pk_fma_f32 v[156:157], v[156:157], v[196:197], v[222:223] op_sel:[0,0,0] op_sel_hi:[1,0,1]
	v_pk_fma_f32 v[226:227], v[156:157], v[216:217], v[226:227] op_sel:[0,0,0] op_sel_hi:[1,0,1]
	s_waitcnt vmcnt(2)
	v_pk_mul_f32 v[224:225], v[204:205], v[208:209] op_sel:[0,1] op_sel_hi:[1,1]
	v_pk_fma_f32 v[158:159], v[158:159], v[196:197], v[224:225] op_sel:[0,1,0] op_sel_hi:[1,1,1]
	v_pk_fma_f32 v[228:229], v[158:159], v[216:217], v[228:229] op_sel:[0,1,0] op_sel_hi:[1,1,1]
	s_waitcnt vmcnt(1)
	v_pk_mul_f32 v[222:223], v[204:205], v[210:211] op_sel:[0,0] op_sel_hi:[1,0]
	v_pk_fma_f32 v[160:161], v[160:161], v[198:199], v[222:223] op_sel:[0,0,0] op_sel_hi:[1,0,1]
	v_pk_fma_f32 v[226:227], v[160:161], v[218:219], v[226:227] op_sel:[0,0,0] op_sel_hi:[1,0,1]
	s_waitcnt vmcnt(0)
	v_pk_mul_f32 v[224:225], v[204:205], v[210:211] op_sel:[0,1] op_sel_hi:[1,1]
	v_pk_fma_f32 v[162:163], v[162:163], v[198:199], v[224:225] op_sel:[0,1,0] op_sel_hi:[1,1,1]
	v_pk_fma_f32 v[228:229], v[162:163], v[218:219], v[228:229] op_sel:[0,1,0] op_sel_hi:[1,1,1]
	v_pk_add_f32 v[226:227], v[226:227], v[228:229]
	ds_write_b64 v235, v[226:227] offset:8192
	ds_read_b128 v[192:195], v233 offset:4640
	ds_read_b128 v[196:199], v233 offset:4656
	ds_read_b128 v[200:203], v233 offset:2592
	ds_read_b128 v[208:211], v233 offset:2608
	ds_read_b128 v[212:215], v233 offset:544
	ds_read_b128 v[216:219], v233 offset:560
	s_waitcnt lgkmcnt(7)
; __device__ __forceinline__ void hgrn_sample_pair(const Params& p, float* lds, int unit) {
;     ...
;         for (int t = 0; t < DS; ++t) { const float vt = sv[t * 128 + v]; float o = 0.f; const float* f_ = sf + t * 128 + 64 * kg; const float* k_ = sk + t * 128 + 64 * kg; const float* q_ = sq + t * 128 + 64 * kg;
; #pragma unroll
;             for (int k = 0; k < 64; ++k) { S[k] = f_[k] * S[k] + k_[k] * vt; o += q_[k] * S[k]; }
;             po[(t * 2 + kg) * 128 + v] = o; }
	v_pk_mul_f32 v[222:223], v[220:221], v[172:173] op_sel:[0,0] op_sel_hi:[1,0]
	v_pk_fma_f32 v[100:101], v[100:101], v[164:165], v[222:223] op_sel:[0,0,0] op_sel_hi:[1,0,1]
	v_pk_mul_f32 v[226:227], v[100:101], v[184:185] op_sel:[0,0] op_sel_hi:[1,0]
	v_pk_mul_f32 v[224:225], v[220:221], v[172:173] op_sel:[0,1] op_sel_hi:[1,1]
	v_pk_fma_f32 v[102:103], v[102:103], v[164:165], v[224:225] op_sel:[0,1,0] op_sel_hi:[1,1,1]
	v_pk_mul_f32 v[228:229], v[102:103], v[184:185] op_sel:[0,1] op_sel_hi:[1,1]
	v_pk_mul_f32 v[222:223], v[220:221], v[174:175] op_sel:[0,0] op_sel_hi:[1,0]
	v_pk_fma_f32 v[104:105], v[104:105], v[166:167], v[222:223] op_sel:[0,0,0] op_sel_hi:[1,0,1]
	v_pk_fma_f32 v[226:227], v[104:105], v[186:187], v[226:227] op_sel:[0,0,0] op_sel_hi:[1,0,1]
	v_pk_mul_f32 v[224:225], v[220:221], v[174:175] op_sel:[0,1] op_sel_hi:[1,1]
	v_pk_fma_f32 v[106:107], v[106:107], v[166:167], v[224:225] op_sel:[0,1,0] op_sel_hi:[1,1,1]
	v_pk_fma_f32 v[228:229], v[106:107], v[186:187], v[228:229] op_sel:[0,1,0] op_sel_hi:[1,1,1]
	v_pk_mul_f32 v[222:223], v[220:221], v[180:181] op_sel:[0,0] op_sel_hi:[1,0]
	v_pk_fma_f32 v[108:109], v[108:109], v[168:169], v[222:223] op_sel:[0,0,0] op_sel_hi:[1,0,1]
	v_pk_fma_f32 v[226:227], v[108:109], v[188:189], v[226:227] op_sel:[0,0,0] op_sel_hi:[1,0,1]
	v_pk_mul_f32 v[224:225], v[220:221], v[180:181] op_sel:[0,1] op_sel_hi:[1,1]
	v_pk_fma_f32 v[110:111], v[110:111], v[168:169], v[224:225] op_sel:[0,1,0] op_sel_hi:[1,1,1]
	v_pk_fma_f32 v[228:229], v[110:111], v[188:189], v[228:229] op_sel:[0,1,0] op_sel_hi:[1,1,1]
	v_pk_mul_f32 v[222:223], v[220:221], v[182:183] op_sel:[0,0] op_sel_hi:[1,0]
	v_pk_fma_f32 v[112:113], v[112:113], v[170:171], v[222:223] op_sel:[0,0,0] op_sel_hi:[1,0,1]
	v_pk_fma_f32 v[226:227], v[112:113], v[190:191], v[226:227] op_sel:[0,0,0] op_sel_hi:[1,0,1]
	v_pk_mul_f32 v[224:225], v[220:221], v[182:183] op_sel:[0,1] op_sel_hi:[1,1]
	v_pk_fma_f32 v[114:115], v[114:115], v[170:171], v[224:225] op_sel:[0,1,0] op_sel_hi:[1,1,1]
	v_pk_fma_f32 v[228:229], v[114:115], v[190:191], v[228:229] op_sel:[0,1,0] op_sel_hi:[1,1,1]
	ds_read_b128 v[164:167], v233 offset:4672
	ds_read_b128 v[168:171], v233 offset:4688
	ds_read_b128 v[172:175], v233 offset:2624
	ds_read_b128 v[180:183], v233 offset:2640
	ds_read_b128 v[184:187], v233 offset:576
	ds_read_b128 v[188:191], v233 offset:592
	s_waitcnt lgkmcnt(6)
	v_pk_mul_f32 v[222:223], v[220:221], v[200:201] op_sel:[0,0] op_sel_hi:[1,0]
	v_pk_fma_f32 v[116:117], v[116:117], v[192:193], v[222:223] op_sel:[0,0,0] op_sel_hi:[1,0,1]
	v_pk_fma_f32 v[226:227], v[116:117], v[212:213], v[226:227] op_sel:[0,0,0] op_sel_hi:[1,0,1]
	v_pk_mul_f32 v[224:225], v[220:221], v[200:201] op_sel:[0,1] op_sel_hi:[1,1]
	v_pk_fma_f32 v[118:119], v[118:119], v[192:193], v[224:225] op_sel:[0,1,0] op_sel_hi:[1,1,1]
	v_pk_fma_f32 v[228:229], v[118:119], v[212:213], v[228:229] op_sel:[0,1,0] op_sel_hi:[1,1,1]
	v_pk_mul_f32 v[222:223], v[220:221], v[202:203] op_sel:[0,0] op_sel_hi:[1,0]
	v_pk_fma_f32 v[120:121], v[120:121], v[194:195], v[222:223] op_sel:[0,0,0] op_sel_hi:[1,0,1]
	v_pk_fma_f32 v[226:227], v[120:121], v[214:215], v[226:227] op_sel:[0,0,0] op_sel_hi:[1,0,1]
	v_pk_mul_f32 v[224:225], v[220:221], v[202:203] op_sel:[0,1] op_sel_hi:[1,1]
	v_pk_fma_f32 v[122:123], v[122:123], v[194:195], v[224:225] op_sel:[0,1,0] op_sel_hi:[1,1,1]
	v_pk_fma_f32 v[228:229], v[122:123], v[214:215], v[228:229] op_sel:[0,1,0] op_sel_hi:[1,1,1]
	v_pk_mul_f32 v[222:223], v[220:221], v[208:209] op_sel:[0,0] op_sel_hi:[1,0]
	v_pk_fma_f32 v[124:125], v[124:125], v[196:197], v[222:223] op_sel:[0,0,0] op_sel_hi:[1,0,1]
	v_pk_fma_f32 v[226:227], v[124:125], v[216:217], v[226:227] op_sel:[0,0,0] op_sel_hi:[1,0,1]
	v_pk_mul_f32 v[224:225], v[220:221], v[208:209] op_sel:[0,1] op_sel_hi:[1,1]
	v_pk_fma_f32 v[126:127], v[126:127], v[196:197], v[224:225] op_sel:[0,1,0] op_sel_hi:[1,1,1]
	v_pk_fma_f32 v[228:229], v[126:127], v[216:217], v[228:229] op_sel:[0,1,0] op_sel_hi:[1,1,1]
	v_pk_mul_f32 v[222:223], v[220:221], v[210:211] op_sel:[0,0] op_sel_hi:[1,0]
	v_pk_fma_f32 v[128:129], v[128:129], v[198:199], v[222:223] op_sel:[0,0,0] op_sel_hi:[1,0,1]
	v_pk_fma_f32 v[226:227], v[128:129], v[218:219], v[226:227] op_sel:[0,0,0] op_sel_hi:[1,0,1]
	v_pk_mul_f32 v[224:225], v[220:221], v[210:211] op_sel:[0,1] op_sel_hi:[1,1]
	v_pk_fma_f32 v[130:131], v[130:131], v[198:199], v[224:225] op_sel:[0,1,0] op_sel_hi:[1,1,1]
	v_pk_fma_f32 v[228:229], v[130:131], v[218:219], v[228:229] op_sel:[0,1,0] op_sel_hi:[1,1,1]
	ds_read_b128 v[192:195], v233 offset:4704
	ds_read_b128 v[196:199], v233 offset:4720
	ds_read_b128 v[200:203], v233 offset:2656
	ds_read_b128 v[208:211], v233 offset:2672
	ds_read_b128 v[212:215], v233 offset:608
	ds_read_b128 v[216:219], v233 offset:624
	s_waitcnt lgkmcnt(6)
; __device__ __forceinline__ void hgrn_sample_pair(const Params& p, float* lds, int unit) {
;     ...
;         for (int t = 0; t < DS; ++t) { const float vt = sv[t * 128 + v]; float o = 0.f; const float* f_ = sf + t * 128 + 64 * kg; const float* k_ = sk + t * 128 + 64 * kg; const float* q_ = sq + t * 128 + 64 * kg;
; #pragma unroll
;             for (int k = 0; k < 64; ++k) { S[k] = f_[k] * S[k] + k_[k] * vt; o += q_[k] * S[k]; }
;             po[(t * 2 + kg) * 128 + v] = o; }
	v_pk_mul_f32 v[222:223], v[220:221], v[172:173] op_sel:[0,0] op_sel_hi:[1,0]
	v_pk_fma_f32 v[132:133], v[132:133], v[164:165], v[222:223] op_sel:[0,0,0] op_sel_hi:[1,0,1]
	v_pk_fma_f32 v[226:227], v[132:133], v[184:185], v[226:227] op_sel:[0,0,0] op_sel_hi:[1,0,1]
	v_pk_mul_f32 v[224:225], v[220:221], v[172:173] op_sel:[0,1] op_sel_hi:[1,1]
	v_pk_fma_f32 v[134:135], v[134:135], v[164:165], v[224:225] op_sel:[0,1,0] op_sel_hi:[1,1,1]
	v_pk_fma_f32 v[228:229], v[134:135], v[184:185], v[228:229] op_sel:[0,1,0] op_sel_hi:[1,1,1]
	v_pk_mul_f32 v[222:223], v[220:221], v[174:175] op_sel:[0,0] op_sel_hi:[1,0]
	v_pk_fma_f32 v[136:137], v[136:137], v[166:167], v[222:223] op_sel:[0,0,0] op_sel_hi:[1,0,1]
	v_pk_fma_f32 v[226:227], v[136:137], v[186:187], v[226:227] op_sel:[0,0,0] op_sel_hi:[1,0,1]
	v_pk_mul_f32 v[224:225], v[220:221], v[174:175] op_sel:[0,1] op_sel_hi:[1,1]
	v_pk_fma_f32 v[138:139], v[138:139], v[166:167], v[224:225] op_sel:[0,1,0] op_sel_hi:[1,1,1]
	v_pk_fma_f32 v[228:229], v[138:139], v[186:187], v[228:229] op_sel:[0,1,0] op_sel_hi:[1,1,1]
	v_pk_mul_f32 v[222:223], v[220:221], v[180:181] op_sel:[0,0] op_sel_hi:[1,0]
	v_pk_fma_f32 v[140:141], v[140:141], v[168:169], v[222:223] op_sel:[0,0,0] op_sel_hi:[1,0,1]
	v_pk_fma_f32 v[226:227], v[140:141], v[188:189], v[226:227] op_sel:[0,0,0] op_sel_hi:[1,0,1]
	v_pk_mul_f32 v[224:225], v[220:221], v[180:181] op_sel:[0,1] op_sel_hi:[1,1]
	v_pk_fma_f32 v[142:143], v[142:143], v[168:169], v[224:225] op_sel:[0,1,0] op_sel_hi:[1,1,1]
	v_pk_fma_f32 v[228:229], v[142:143], v[188:189], v[228:229] op_sel:[0,1,0] op_sel_hi:[1,1,1]
	v_pk_mul_f32 v[222:223], v[220:221], v[182:183] op_sel:[0,0] op_sel_hi:[1,0]
	v_pk_fma_f32 v[144:145], v[144:145], v[170:171], v[222:223] op_sel:[0,0,0] op_sel_hi:[1,0,1]
	v_pk_fma_f32 v[226:227], v[144:145], v[190:191], v[226:227] op_sel:[0,0,0] op_sel_hi:[1,0,1]
	v_pk_mul_f32 v[224:225], v[220:221], v[182:183] op_sel:[0,1] op_sel_hi:[1,1]
	v_pk_fma_f32 v[146:147], v[146:147], v[170:171], v[224:225] op_sel:[0,1,0] op_sel_hi:[1,1,1]
	v_pk_fma_f32 v[228:229], v[146:147], v[190:191], v[228:229] op_sel:[0,1,0] op_sel_hi:[1,1,1]
	ds_read_b64 v[204:205], v234 offset:7168
	ds_read_b128 v[164:167], v233 offset:5120
	ds_read_b128 v[168:171], v233 offset:5136
	ds_read_b128 v[172:175], v233 offset:3072
	ds_read_b128 v[180:183], v233 offset:3088
	ds_read_b128 v[184:187], v233 offset:1024
	ds_read_b128 v[188:191], v233 offset:1040
	s_waitcnt lgkmcnt(7)
	v_pk_mul_f32 v[222:223], v[220:221], v[200:201] op_sel:[0,0] op_sel_hi:[1,0]
	v_pk_fma_f32 v[148:149], v[148:149], v[192:193], v[222:223] op_sel:[0,0,0] op_sel_hi:[1,0,1]
	v_pk_fma_f32 v[226:227], v[148:149], v[212:213], v[226:227] op_sel:[0,0,0] op_sel_hi:[1,0,1]
	v_pk_mul_f32 v[224:225], v[220:221], v[200:201] op_sel:[0,1] op_sel_hi:[1,1]
	v_pk_fma_f32 v[150:151], v[150:151], v[192:193], v[224:225] op_sel:[0,1,0] op_sel_hi:[1,1,1]
	v_pk_fma_f32 v[228:229], v[150:151], v[212:213], v[228:229] op_sel:[0,1,0] op_sel_hi:[1,1,1]
	v_pk_mul_f32 v[222:223], v[220:221], v[202:203] op_sel:[0,0] op_sel_hi:[1,0]
	v_pk_fma_f32 v[152:153], v[152:153], v[194:195], v[222:223] op_sel:[0,0,0] op_sel_hi:[1,0,1]
	v_pk_fma_f32 v[226:227], v[152:153], v[214:215], v[226:227] op_sel:[0,0,0] op_sel_hi:[1,0,1]
	v_pk_mul_f32 v[224:225], v[220:221], v[202:203] op_sel:[0,1] op_sel_hi:[1,1]
	v_pk_fma_f32 v[154:155], v[154:155], v[194:195], v[224:225] op_sel:[0,1,0] op_sel_hi:[1,1,1]
	v_pk_fma_f32 v[228:229], v[154:155], v[214:215], v[228:229] op_sel:[0,1,0] op_sel_hi:[1,1,1]
	v_pk_mul_f32 v[222:223], v[220:221], v[208:209] op_sel:[0,0] op_sel_hi:[1,0]
	v_pk_fma_f32 v[156:157], v[156:157], v[196:197], v[222:223] op_sel:[0,0,0] op_sel_hi:[1,0,1]
	v_pk_fma_f32 v[226:227], v[156:157], v[216:217], v[226:227] op_sel:[0,0,0] op_sel_hi:[1,0,1]
	v_pk_mul_f32 v[224:225], v[220:221], v[208:209] op_sel:[0,1] op_sel_hi:[1,1]
	v_pk_fma_f32 v[158:159], v[158:159], v[196:197], v[224:225] op_sel:[0,1,0] op_sel_hi:[1,1,1]
	v_pk_fma_f32 v[228:229], v[158:159], v[216:217], v[228:229] op_sel:[0,1,0] op_sel_hi:[1,1,1]
	v_pk_mul_f32 v[222:223], v[220:221], v[210:211] op_sel:[0,0] op_sel_hi:[1,0]
	v_pk_fma_f32 v[160:161], v[160:161], v[198:199], v[222:223] op_sel:[0,0,0] op_sel_hi:[1,0,1]
	v_pk_fma_f32 v[226:227], v[160:161], v[218:219], v[226:227] op_sel:[0,0,0] op_sel_hi:[1,0,1]
	v_pk_mul_f32 v[224:225], v[220:221], v[210:211] op_sel:[0,1] op_sel_hi:[1,1]
	v_pk_fma_f32 v[162:163], v[162:163], v[198:199], v[224:225] op_sel:[0,1,0] op_sel_hi:[1,1,1]
	v_pk_fma_f32 v[228:229], v[162:163], v[218:219], v[228:229] op_sel:[0,1,0] op_sel_hi:[1,1,1]
	v_pk_add_f32 v[226:227], v[226:227], v[228:229]
	ds_write_b64 v235, v[226:227] offset:10240
	ds_read_b128 v[192:195], v233 offset:5152
	ds_read_b128 v[196:199], v233 offset:5168
	ds_read_b128 v[200:203], v233 offset:3104
	ds_read_b128 v[208:211], v233 offset:3120
	ds_read_b128 v[212:215], v233 offset:1056
	ds_read_b128 v[216:219], v233 offset:1072
	s_waitcnt lgkmcnt(7)
; __device__ __forceinline__ void hgrn_sample_pair(const Params& p, float* lds, int unit) {
;     ...
;         for (int t = 0; t < DS; ++t) { const float vt = sv[t * 128 + v]; float o = 0.f; const float* f_ = sf + t * 128 + 64 * kg; const float* k_ = sk + t * 128 + 64 * kg; const float* q_ = sq + t * 128 + 64 * kg;
; #pragma unroll
;             for (int k = 0; k < 64; ++k) { S[k] = f_[k] * S[k] + k_[k] * vt; o += q_[k] * S[k]; }
;             po[(t * 2 + kg) * 128 + v] = o; }
	v_pk_mul_f32 v[222:223], v[204:205], v[172:173] op_sel:[0,0] op_sel_hi:[1,0]
	v_pk_fma_f32 v[100:101], v[100:101], v[164:165], v[222:223] op_sel:[0,0,0] op_sel_hi:[1,0,1]
	v_pk_mul_f32 v[226:227], v[100:101], v[184:185] op_sel:[0,0] op_sel_hi:[1,0]
	v_pk_mul_f32 v[224:225], v[204:205], v[172:173] op_sel:[0,1] op_sel_hi:[1,1]
	v_pk_fma_f32 v[102:103], v[102:103], v[164:165], v[224:225] op_sel:[0,1,0] op_sel_hi:[1,1,1]
	v_pk_mul_f32 v[228:229], v[102:103], v[184:185] op_sel:[0,1] op_sel_hi:[1,1]
	v_pk_mul_f32 v[222:223], v[204:205], v[174:175] op_sel:[0,0] op_sel_hi:[1,0]
	v_pk_fma_f32 v[104:105], v[104:105], v[166:167], v[222:223] op_sel:[0,0,0] op_sel_hi:[1,0,1]
	v_pk_fma_f32 v[226:227], v[104:105], v[186:187], v[226:227] op_sel:[0,0,0] op_sel_hi:[1,0,1]
	v_pk_mul_f32 v[224:225], v[204:205], v[174:175] op_sel:[0,1] op_sel_hi:[1,1]
	v_pk_fma_f32 v[106:107], v[106:107], v[166:167], v[224:225] op_sel:[0,1,0] op_sel_hi:[1,1,1]
	v_pk_fma_f32 v[228:229], v[106:107], v[186:187], v[228:229] op_sel:[0,1,0] op_sel_hi:[1,1,1]
	v_pk_mul_f32 v[222:223], v[204:205], v[180:181] op_sel:[0,0] op_sel_hi:[1,0]
	v_pk_fma_f32 v[108:109], v[108:109], v[168:169], v[222:223] op_sel:[0,0,0] op_sel_hi:[1,0,1]
	v_pk_fma_f32 v[226:227], v[108:109], v[188:189], v[226:227] op_sel:[0,0,0] op_sel_hi:[1,0,1]
	v_pk_mul_f32 v[224:225], v[204:205], v[180:181] op_sel:[0,1] op_sel_hi:[1,1]
	v_pk_fma_f32 v[110:111], v[110:111], v[168:169], v[224:225] op_sel:[0,1,0] op_sel_hi:[1,1,1]
	v_pk_fma_f32 v[228:229], v[110:111], v[188:189], v[228:229] op_sel:[0,1,0] op_sel_hi:[1,1,1]
	v_pk_mul_f32 v[222:223], v[204:205], v[182:183] op_sel:[0,0] op_sel_hi:[1,0]
	v_pk_fma_f32 v[112:113], v[112:113], v[170:171], v[222:223] op_sel:[0,0,0] op_sel_hi:[1,0,1]
	v_pk_fma_f32 v[226:227], v[112:113], v[190:191], v[226:227] op_sel:[0,0,0] op_sel_hi:[1,0,1]
	v_pk_mul_f32 v[224:225], v[204:205], v[182:183] op_sel:[0,1] op_sel_hi:[1,1]
	v_pk_fma_f32 v[114:115], v[114:115], v[170:171], v[224:225] op_sel:[0,1,0] op_sel_hi:[1,1,1]
	v_pk_fma_f32 v[228:229], v[114:115], v[190:191], v[228:229] op_sel:[0,1,0] op_sel_hi:[1,1,1]
	ds_read_b128 v[164:167], v233 offset:5184
	ds_read_b128 v[168:171], v233 offset:5200
	ds_read_b128 v[172:175], v233 offset:3136
	ds_read_b128 v[180:183], v233 offset:3152
	ds_read_b128 v[184:187], v233 offset:1088
	ds_read_b128 v[188:191], v233 offset:1104
	s_waitcnt lgkmcnt(6)
	v_pk_mul_f32 v[222:223], v[204:205], v[200:201] op_sel:[0,0] op_sel_hi:[1,0]
	v_pk_fma_f32 v[116:117], v[116:117], v[192:193], v[222:223] op_sel:[0,0,0] op_sel_hi:[1,0,1]
	v_pk_fma_f32 v[226:227], v[116:117], v[212:213], v[226:227] op_sel:[0,0,0] op_sel_hi:[1,0,1]
	v_pk_mul_f32 v[224:225], v[204:205], v[200:201] op_sel:[0,1] op_sel_hi:[1,1]
	v_pk_fma_f32 v[118:119], v[118:119], v[192:193], v[224:225] op_sel:[0,1,0] op_sel_hi:[1,1,1]
	v_pk_fma_f32 v[228:229], v[118:119], v[212:213], v[228:229] op_sel:[0,1,0] op_sel_hi:[1,1,1]
	v_pk_mul_f32 v[222:223], v[204:205], v[202:203] op_sel:[0,0] op_sel_hi:[1,0]
	v_pk_fma_f32 v[120:121], v[120:121], v[194:195], v[222:223] op_sel:[0,0,0] op_sel_hi:[1,0,1]
	v_pk_fma_f32 v[226:227], v[120:121], v[214:215], v[226:227] op_sel:[0,0,0] op_sel_hi:[1,0,1]
	v_pk_mul_f32 v[224:225], v[204:205], v[202:203] op_sel:[0,1] op_sel_hi:[1,1]
	v_pk_fma_f32 v[122:123], v[122:123], v[194:195], v[224:225] op_sel:[0,1,0] op_sel_hi:[1,1,1]
	v_pk_fma_f32 v[228:229], v[122:123], v[214:215], v[228:229] op_sel:[0,1,0] op_sel_hi:[1,1,1]
	v_pk_mul_f32 v[222:223], v[204:205], v[208:209] op_sel:[0,0] op_sel_hi:[1,0]
	v_pk_fma_f32 v[124:125], v[124:125], v[196:197], v[222:223] op_sel:[0,0,0] op_sel_hi:[1,0,1]
	v_pk_fma_f32 v[226:227], v[124:125], v[216:217], v[226:227] op_sel:[0,0,0] op_sel_hi:[1,0,1]
	v_pk_mul_f32 v[224:225], v[204:205], v[208:209] op_sel:[0,1] op_sel_hi:[1,1]
	v_pk_fma_f32 v[126:127], v[126:127], v[196:197], v[224:225] op_sel:[0,1,0] op_sel_hi:[1,1,1]
	v_pk_fma_f32 v[228:229], v[126:127], v[216:217], v[228:229] op_sel:[0,1,0] op_sel_hi:[1,1,1]
	v_pk_mul_f32 v[222:223], v[204:205], v[210:211] op_sel:[0,0] op_sel_hi:[1,0]
	v_pk_fma_f32 v[128:129], v[128:129], v[198:199], v[222:223] op_sel:[0,0,0] op_sel_hi:[1,0,1]
	v_pk_fma_f32 v[226:227], v[128:129], v[218:219], v[226:227] op_sel:[0,0,0] op_sel_hi:[1,0,1]
	v_pk_mul_f32 v[224:225], v[204:205], v[210:211] op_sel:[0,1] op_sel_hi:[1,1]
	v_pk_fma_f32 v[130:131], v[130:131], v[198:199], v[224:225] op_sel:[0,1,0] op_sel_hi:[1,1,1]
	v_pk_fma_f32 v[228:229], v[130:131], v[218:219], v[228:229] op_sel:[0,1,0] op_sel_hi:[1,1,1]
	ds_read_b128 v[192:195], v233 offset:5216
	ds_read_b128 v[196:199], v233 offset:5232
	ds_read_b128 v[200:203], v233 offset:3168
	ds_read_b128 v[208:211], v233 offset:3184
	ds_read_b128 v[212:215], v233 offset:1120
	ds_read_b128 v[216:219], v233 offset:1136
	s_waitcnt lgkmcnt(6)
; __device__ __forceinline__ void hgrn_sample_pair(const Params& p, float* lds, int unit) {
;     ...
;         for (int t = 0; t < DS; ++t) { const float vt = sv[t * 128 + v]; float o = 0.f; const float* f_ = sf + t * 128 + 64 * kg; const float* k_ = sk + t * 128 + 64 * kg; const float* q_ = sq + t * 128 + 64 * kg;
; #pragma unroll
;             for (int k = 0; k < 64; ++k) { S[k] = f_[k] * S[k] + k_[k] * vt; o += q_[k] * S[k]; }
;             po[(t * 2 + kg) * 128 + v] = o; }
	v_pk_mul_f32 v[222:223], v[204:205], v[172:173] op_sel:[0,0] op_sel_hi:[1,0]
	v_pk_fma_f32 v[132:133], v[132:133], v[164:165], v[222:223] op_sel:[0,0,0] op_sel_hi:[1,0,1]
	v_pk_fma_f32 v[226:227], v[132:133], v[184:185], v[226:227] op_sel:[0,0,0] op_sel_hi:[1,0,1]
	v_pk_mul_f32 v[224:225], v[204:205], v[172:173] op_sel:[0,1] op_sel_hi:[1,1]
	v_pk_fma_f32 v[134:135], v[134:135], v[164:165], v[224:225] op_sel:[0,1,0] op_sel_hi:[1,1,1]
	v_pk_fma_f32 v[228:229], v[134:135], v[184:185], v[228:229] op_sel:[0,1,0] op_sel_hi:[1,1,1]
	v_pk_mul_f32 v[222:223], v[204:205], v[174:175] op_sel:[0,0] op_sel_hi:[1,0]
	v_pk_fma_f32 v[136:137], v[136:137], v[166:167], v[222:223] op_sel:[0,0,0] op_sel_hi:[1,0,1]
	v_pk_fma_f32 v[226:227], v[136:137], v[186:187], v[226:227] op_sel:[0,0,0] op_sel_hi:[1,0,1]
	v_pk_mul_f32 v[224:225], v[204:205], v[174:175] op_sel:[0,1] op_sel_hi:[1,1]
	v_pk_fma_f32 v[138:139], v[138:139], v[166:167], v[224:225] op_sel:[0,1,0] op_sel_hi:[1,1,1]
	v_pk_fma_f32 v[228:229], v[138:139], v[186:187], v[228:229] op_sel:[0,1,0] op_sel_hi:[1,1,1]
	v_pk_mul_f32 v[222:223], v[204:205], v[180:181] op_sel:[0,0] op_sel_hi:[1,0]
	v_pk_fma_f32 v[140:141], v[140:141], v[168:169], v[222:223] op_sel:[0,0,0] op_sel_hi:[1,0,1]
	v_pk_fma_f32 v[226:227], v[140:141], v[188:189], v[226:227] op_sel:[0,0,0] op_sel_hi:[1,0,1]
	v_pk_mul_f32 v[224:225], v[204:205], v[180:181] op_sel:[0,1] op_sel_hi:[1,1]
	v_pk_fma_f32 v[142:143], v[142:143], v[168:169], v[224:225] op_sel:[0,1,0] op_sel_hi:[1,1,1]
	v_pk_fma_f32 v[228:229], v[142:143], v[188:189], v[228:229] op_sel:[0,1,0] op_sel_hi:[1,1,1]
	v_pk_mul_f32 v[222:223], v[204:205], v[182:183] op_sel:[0,0] op_sel_hi:[1,0]
	v_pk_fma_f32 v[144:145], v[144:145], v[170:171], v[222:223] op_sel:[0,0,0] op_sel_hi:[1,0,1]
	v_pk_fma_f32 v[226:227], v[144:145], v[190:191], v[226:227] op_sel:[0,0,0] op_sel_hi:[1,0,1]
	v_pk_mul_f32 v[224:225], v[204:205], v[182:183] op_sel:[0,1] op_sel_hi:[1,1]
	v_pk_fma_f32 v[146:147], v[146:147], v[170:171], v[224:225] op_sel:[0,1,0] op_sel_hi:[1,1,1]
	v_pk_fma_f32 v[228:229], v[146:147], v[190:191], v[228:229] op_sel:[0,1,0] op_sel_hi:[1,1,1]
	ds_read_b64 v[220:221], v234 offset:7680
	ds_read_b128 v[164:167], v233 offset:5632
	ds_read_b128 v[168:171], v233 offset:5648
	ds_read_b128 v[172:175], v233 offset:3584
	ds_read_b128 v[180:183], v233 offset:3600
	ds_read_b128 v[184:187], v233 offset:1536
	ds_read_b128 v[188:191], v233 offset:1552
	s_waitcnt lgkmcnt(7)
	v_pk_mul_f32 v[222:223], v[204:205], v[200:201] op_sel:[0,0] op_sel_hi:[1,0]
	v_pk_fma_f32 v[148:149], v[148:149], v[192:193], v[222:223] op_sel:[0,0,0] op_sel_hi:[1,0,1]
	v_pk_fma_f32 v[226:227], v[148:149], v[212:213], v[226:227] op_sel:[0,0,0] op_sel_hi:[1,0,1]
	v_pk_mul_f32 v[224:225], v[204:205], v[200:201] op_sel:[0,1] op_sel_hi:[1,1]
	v_pk_fma_f32 v[150:151], v[150:151], v[192:193], v[224:225] op_sel:[0,1,0] op_sel_hi:[1,1,1]
	v_pk_fma_f32 v[228:229], v[150:151], v[212:213], v[228:229] op_sel:[0,1,0] op_sel_hi:[1,1,1]
	v_pk_mul_f32 v[222:223], v[204:205], v[202:203] op_sel:[0,0] op_sel_hi:[1,0]
	v_pk_fma_f32 v[152:153], v[152:153], v[194:195], v[222:223] op_sel:[0,0,0] op_sel_hi:[1,0,1]
	v_pk_fma_f32 v[226:227], v[152:153], v[214:215], v[226:227] op_sel:[0,0,0] op_sel_hi:[1,0,1]
	v_pk_mul_f32 v[224:225], v[204:205], v[202:203] op_sel:[0,1] op_sel_hi:[1,1]
	v_pk_fma_f32 v[154:155], v[154:155], v[194:195], v[224:225] op_sel:[0,1,0] op_sel_hi:[1,1,1]
	v_pk_fma_f32 v[228:229], v[154:155], v[214:215], v[228:229] op_sel:[0,1,0] op_sel_hi:[1,1,1]
	v_pk_mul_f32 v[222:223], v[204:205], v[208:209] op_sel:[0,0] op_sel_hi:[1,0]
	v_pk_fma_f32 v[156:157], v[156:157], v[196:197], v[222:223] op_sel:[0,0,0] op_sel_hi:[1,0,1]
	v_pk_fma_f32 v[226:227], v[156:157], v[216:217], v[226:227] op_sel:[0,0,0] op_sel_hi:[1,0,1]
	v_pk_mul_f32 v[224:225], v[204:205], v[208:209] op_sel:[0,1] op_sel_hi:[1,1]
	v_pk_fma_f32 v[158:159], v[158:159], v[196:197], v[224:225] op_sel:[0,1,0] op_sel_hi:[1,1,1]
	v_pk_fma_f32 v[228:229], v[158:159], v[216:217], v[228:229] op_sel:[0,1,0] op_sel_hi:[1,1,1]
	v_pk_mul_f32 v[222:223], v[204:205], v[210:211] op_sel:[0,0] op_sel_hi:[1,0]
	v_pk_fma_f32 v[160:161], v[160:161], v[198:199], v[222:223] op_sel:[0,0,0] op_sel_hi:[1,0,1]
	v_pk_fma_f32 v[226:227], v[160:161], v[218:219], v[226:227] op_sel:[0,0,0] op_sel_hi:[1,0,1]
	v_pk_mul_f32 v[224:225], v[204:205], v[210:211] op_sel:[0,1] op_sel_hi:[1,1]
	v_pk_fma_f32 v[162:163], v[162:163], v[198:199], v[224:225] op_sel:[0,1,0] op_sel_hi:[1,1,1]
	v_pk_fma_f32 v[228:229], v[162:163], v[218:219], v[228:229] op_sel:[0,1,0] op_sel_hi:[1,1,1]
	v_pk_add_f32 v[226:227], v[226:227], v[228:229]
	ds_write_b64 v235, v[226:227] offset:12288
	ds_read_b128 v[192:195], v233 offset:5664
	ds_read_b128 v[196:199], v233 offset:5680
	ds_read_b128 v[200:203], v233 offset:3616
	ds_read_b128 v[208:211], v233 offset:3632
	ds_read_b128 v[212:215], v233 offset:1568
	ds_read_b128 v[216:219], v233 offset:1584
	s_waitcnt lgkmcnt(7)
; __device__ __forceinline__ void hgrn_sample_pair(const Params& p, float* lds, int unit) {
;     ...
;         for (int t = 0; t < DS; ++t) { const float vt = sv[t * 128 + v]; float o = 0.f; const float* f_ = sf + t * 128 + 64 * kg; const float* k_ = sk + t * 128 + 64 * kg; const float* q_ = sq + t * 128 + 64 * kg;
; #pragma unroll
;             for (int k = 0; k < 64; ++k) { S[k] = f_[k] * S[k] + k_[k] * vt; o += q_[k] * S[k]; }
;             po[(t * 2 + kg) * 128 + v] = o; }
	v_pk_mul_f32 v[222:223], v[220:221], v[172:173] op_sel:[0,0] op_sel_hi:[1,0]
	v_pk_fma_f32 v[100:101], v[100:101], v[164:165], v[222:223] op_sel:[0,0,0] op_sel_hi:[1,0,1]
	v_pk_mul_f32 v[226:227], v[100:101], v[184:185] op_sel:[0,0] op_sel_hi:[1,0]
	v_pk_mul_f32 v[224:225], v[220:221], v[172:173] op_sel:[0,1] op_sel_hi:[1,1]
	v_pk_fma_f32 v[102:103], v[102:103], v[164:165], v[224:225] op_sel:[0,1,0] op_sel_hi:[1,1,1]
	v_pk_mul_f32 v[228:229], v[102:103], v[184:185] op_sel:[0,1] op_sel_hi:[1,1]
	v_pk_mul_f32 v[222:223], v[220:221], v[174:175] op_sel:[0,0] op_sel_hi:[1,0]
	v_pk_fma_f32 v[104:105], v[104:105], v[166:167], v[222:223] op_sel:[0,0,0] op_sel_hi:[1,0,1]
	v_pk_fma_f32 v[226:227], v[104:105], v[186:187], v[226:227] op_sel:[0,0,0] op_sel_hi:[1,0,1]
	v_pk_mul_f32 v[224:225], v[220:221], v[174:175] op_sel:[0,1] op_sel_hi:[1,1]
	v_pk_fma_f32 v[106:107], v[106:107], v[166:167], v[224:225] op_sel:[0,1,0] op_sel_hi:[1,1,1]
	v_pk_fma_f32 v[228:229], v[106:107], v[186:187], v[228:229] op_sel:[0,1,0] op_sel_hi:[1,1,1]
	v_pk_mul_f32 v[222:223], v[220:221], v[180:181] op_sel:[0,0] op_sel_hi:[1,0]
	v_pk_fma_f32 v[108:109], v[108:109], v[168:169], v[222:223] op_sel:[0,0,0] op_sel_hi:[1,0,1]
	v_pk_fma_f32 v[226:227], v[108:109], v[188:189], v[226:227] op_sel:[0,0,0] op_sel_hi:[1,0,1]
	v_pk_mul_f32 v[224:225], v[220:221], v[180:181] op_sel:[0,1] op_sel_hi:[1,1]
	v_pk_fma_f32 v[110:111], v[110:111], v[168:169], v[224:225] op_sel:[0,1,0] op_sel_hi:[1,1,1]
	v_pk_fma_f32 v[228:229], v[110:111], v[188:189], v[228:229] op_sel:[0,1,0] op_sel_hi:[1,1,1]
	v_pk_mul_f32 v[222:223], v[220:221], v[182:183] op_sel:[0,0] op_sel_hi:[1,0]
	v_pk_fma_f32 v[112:113], v[112:113], v[170:171], v[222:223] op_sel:[0,0,0] op_sel_hi:[1,0,1]
	v_pk_fma_f32 v[226:227], v[112:113], v[190:191], v[226:227] op_sel:[0,0,0] op_sel_hi:[1,0,1]
	v_pk_mul_f32 v[224:225], v[220:221], v[182:183] op_sel:[0,1] op_sel_hi:[1,1]
	v_pk_fma_f32 v[114:115], v[114:115], v[170:171], v[224:225] op_sel:[0,1,0] op_sel_hi:[1,1,1]
	v_pk_fma_f32 v[228:229], v[114:115], v[190:191], v[228:229] op_sel:[0,1,0] op_sel_hi:[1,1,1]
	ds_read_b128 v[164:167], v233 offset:5696
	ds_read_b128 v[168:171], v233 offset:5712
	ds_read_b128 v[172:175], v233 offset:3648
	ds_read_b128 v[180:183], v233 offset:3664
	ds_read_b128 v[184:187], v233 offset:1600
	ds_read_b128 v[188:191], v233 offset:1616
	s_waitcnt lgkmcnt(6)
	v_pk_mul_f32 v[222:223], v[220:221], v[200:201] op_sel:[0,0] op_sel_hi:[1,0]
	v_pk_fma_f32 v[116:117], v[116:117], v[192:193], v[222:223] op_sel:[0,0,0] op_sel_hi:[1,0,1]
	v_pk_fma_f32 v[226:227], v[116:117], v[212:213], v[226:227] op_sel:[0,0,0] op_sel_hi:[1,0,1]
	v_pk_mul_f32 v[224:225], v[220:221], v[200:201] op_sel:[0,1] op_sel_hi:[1,1]
	v_pk_fma_f32 v[118:119], v[118:119], v[192:193], v[224:225] op_sel:[0,1,0] op_sel_hi:[1,1,1]
	v_pk_fma_f32 v[228:229], v[118:119], v[212:213], v[228:229] op_sel:[0,1,0] op_sel_hi:[1,1,1]
	v_pk_mul_f32 v[222:223], v[220:221], v[202:203] op_sel:[0,0] op_sel_hi:[1,0]
	v_pk_fma_f32 v[120:121], v[120:121], v[194:195], v[222:223] op_sel:[0,0,0] op_sel_hi:[1,0,1]
	v_pk_fma_f32 v[226:227], v[120:121], v[214:215], v[226:227] op_sel:[0,0,0] op_sel_hi:[1,0,1]
	v_pk_mul_f32 v[224:225], v[220:221], v[202:203] op_sel:[0,1] op_sel_hi:[1,1]
	v_pk_fma_f32 v[122:123], v[122:123], v[194:195], v[224:225] op_sel:[0,1,0] op_sel_hi:[1,1,1]
	v_pk_fma_f32 v[228:229], v[122:123], v[214:215], v[228:229] op_sel:[0,1,0] op_sel_hi:[1,1,1]
	v_pk_mul_f32 v[222:223], v[220:221], v[208:209] op_sel:[0,0] op_sel_hi:[1,0]
	v_pk_fma_f32 v[124:125], v[124:125], v[196:197], v[222:223] op_sel:[0,0,0] op_sel_hi:[1,0,1]
	v_pk_fma_f32 v[226:227], v[124:125], v[216:217], v[226:227] op_sel:[0,0,0] op_sel_hi:[1,0,1]
	v_pk_mul_f32 v[224:225], v[220:221], v[208:209] op_sel:[0,1] op_sel_hi:[1,1]
	v_pk_fma_f32 v[126:127], v[126:127], v[196:197], v[224:225] op_sel:[0,1,0] op_sel_hi:[1,1,1]
	v_pk_fma_f32 v[228:229], v[126:127], v[216:217], v[228:229] op_sel:[0,1,0] op_sel_hi:[1,1,1]
	v_pk_mul_f32 v[222:223], v[220:221], v[210:211] op_sel:[0,0] op_sel_hi:[1,0]
	v_pk_fma_f32 v[128:129], v[128:129], v[198:199], v[222:223] op_sel:[0,0,0] op_sel_hi:[1,0,1]
	v_pk_fma_f32 v[226:227], v[128:129], v[218:219], v[226:227] op_sel:[0,0,0] op_sel_hi:[1,0,1]
	v_pk_mul_f32 v[224:225], v[220:221], v[210:211] op_sel:[0,1] op_sel_hi:[1,1]
	v_pk_fma_f32 v[130:131], v[130:131], v[198:199], v[224:225] op_sel:[0,1,0] op_sel_hi:[1,1,1]
	v_pk_fma_f32 v[228:229], v[130:131], v[218:219], v[228:229] op_sel:[0,1,0] op_sel_hi:[1,1,1]
	ds_read_b128 v[192:195], v233 offset:5728
	ds_read_b128 v[196:199], v233 offset:5744
	ds_read_b128 v[200:203], v233 offset:3680
	ds_read_b128 v[208:211], v233 offset:3696
	ds_read_b128 v[212:215], v233 offset:1632
	ds_read_b128 v[216:219], v233 offset:1648
	s_waitcnt lgkmcnt(6)
; __device__ __forceinline__ void hgrn_sample_pair(const Params& p, float* lds, int unit) {
;     ...
;         for (int t = 0; t < DS; ++t) { const float vt = sv[t * 128 + v]; float o = 0.f; const float* f_ = sf + t * 128 + 64 * kg; const float* k_ = sk + t * 128 + 64 * kg; const float* q_ = sq + t * 128 + 64 * kg;
; #pragma unroll
;             for (int k = 0; k < 64; ++k) { S[k] = f_[k] * S[k] + k_[k] * vt; o += q_[k] * S[k]; }
;             po[(t * 2 + kg) * 128 + v] = o; }
;         float* so = p.out + O_SHS + ((size_t)(n * HEADS + h) * DK) * DV + (size_t)(64 * kg) * DV + v;
; #pragma unroll
;         for (int k = 0; k < 64; ++k) __builtin_nontemporal_store(S[k], so + (size_t)k * DV);
;     }
	v_pk_mul_f32 v[222:223], v[220:221], v[172:173] op_sel:[0,0] op_sel_hi:[1,0]
	v_pk_fma_f32 v[132:133], v[132:133], v[164:165], v[222:223] op_sel:[0,0,0] op_sel_hi:[1,0,1]
	v_pk_fma_f32 v[226:227], v[132:133], v[184:185], v[226:227] op_sel:[0,0,0] op_sel_hi:[1,0,1]
	v_pk_mul_f32 v[224:225], v[220:221], v[172:173] op_sel:[0,1] op_sel_hi:[1,1]
	v_pk_fma_f32 v[134:135], v[134:135], v[164:165], v[224:225] op_sel:[0,1,0] op_sel_hi:[1,1,1]
	v_pk_fma_f32 v[228:229], v[134:135], v[184:185], v[228:229] op_sel:[0,1,0] op_sel_hi:[1,1,1]
	v_pk_mul_f32 v[222:223], v[220:221], v[174:175] op_sel:[0,0] op_sel_hi:[1,0]
	v_pk_fma_f32 v[136:137], v[136:137], v[166:167], v[222:223] op_sel:[0,0,0] op_sel_hi:[1,0,1]
	v_pk_fma_f32 v[226:227], v[136:137], v[186:187], v[226:227] op_sel:[0,0,0] op_sel_hi:[1,0,1]
	v_pk_mul_f32 v[224:225], v[220:221], v[174:175] op_sel:[0,1] op_sel_hi:[1,1]
	v_pk_fma_f32 v[138:139], v[138:139], v[166:167], v[224:225] op_sel:[0,1,0] op_sel_hi:[1,1,1]
	v_pk_fma_f32 v[228:229], v[138:139], v[186:187], v[228:229] op_sel:[0,1,0] op_sel_hi:[1,1,1]
	v_pk_mul_f32 v[222:223], v[220:221], v[180:181] op_sel:[0,0] op_sel_hi:[1,0]
	v_pk_fma_f32 v[140:141], v[140:141], v[168:169], v[222:223] op_sel:[0,0,0] op_sel_hi:[1,0,1]
	v_pk_fma_f32 v[226:227], v[140:141], v[188:189], v[226:227] op_sel:[0,0,0] op_sel_hi:[1,0,1]
	v_pk_mul_f32 v[224:225], v[220:221], v[180:181] op_sel:[0,1] op_sel_hi:[1,1]
	v_pk_fma_f32 v[142:143], v[142:143], v[168:169], v[224:225] op_sel:[0,1,0] op_sel_hi:[1,1,1]
	v_pk_fma_f32 v[228:229], v[142:143], v[188:189], v[228:229] op_sel:[0,1,0] op_sel_hi:[1,1,1]
	v_pk_mul_f32 v[222:223], v[220:221], v[182:183] op_sel:[0,0] op_sel_hi:[1,0]
	v_pk_fma_f32 v[144:145], v[144:145], v[170:171], v[222:223] op_sel:[0,0,0] op_sel_hi:[1,0,1]
	v_pk_fma_f32 v[226:227], v[144:145], v[190:191], v[226:227] op_sel:[0,0,0] op_sel_hi:[1,0,1]
	v_pk_mul_f32 v[224:225], v[220:221], v[182:183] op_sel:[0,1] op_sel_hi:[1,1]
	v_pk_fma_f32 v[146:147], v[146:147], v[170:171], v[224:225] op_sel:[0,1,0] op_sel_hi:[1,1,1]
	v_pk_fma_f32 v[228:229], v[146:147], v[190:191], v[228:229] op_sel:[0,1,0] op_sel_hi:[1,1,1]
	s_waitcnt lgkmcnt(0)
	v_pk_mul_f32 v[222:223], v[220:221], v[200:201] op_sel:[0,0] op_sel_hi:[1,0]
	v_pk_fma_f32 v[148:149], v[148:149], v[192:193], v[222:223] op_sel:[0,0,0] op_sel_hi:[1,0,1]
	v_pk_fma_f32 v[226:227], v[148:149], v[212:213], v[226:227] op_sel:[0,0,0] op_sel_hi:[1,0,1]
	v_pk_mul_f32 v[224:225], v[220:221], v[200:201] op_sel:[0,1] op_sel_hi:[1,1]
	v_pk_fma_f32 v[150:151], v[150:151], v[192:193], v[224:225] op_sel:[0,1,0] op_sel_hi:[1,1,1]
	v_pk_fma_f32 v[228:229], v[150:151], v[212:213], v[228:229] op_sel:[0,1,0] op_sel_hi:[1,1,1]
	v_pk_mul_f32 v[222:223], v[220:221], v[202:203] op_sel:[0,0] op_sel_hi:[1,0]
	v_pk_fma_f32 v[152:153], v[152:153], v[194:195], v[222:223] op_sel:[0,0,0] op_sel_hi:[1,0,1]
	v_pk_fma_f32 v[226:227], v[152:153], v[214:215], v[226:227] op_sel:[0,0,0] op_sel_hi:[1,0,1]
	v_pk_mul_f32 v[224:225], v[220:221], v[202:203] op_sel:[0,1] op_sel_hi:[1,1]
	v_pk_fma_f32 v[154:155], v[154:155], v[194:195], v[224:225] op_sel:[0,1,0] op_sel_hi:[1,1,1]
	v_pk_fma_f32 v[228:229], v[154:155], v[214:215], v[228:229] op_sel:[0,1,0] op_sel_hi:[1,1,1]
	v_pk_mul_f32 v[222:223], v[220:221], v[208:209] op_sel:[0,0] op_sel_hi:[1,0]
	v_pk_fma_f32 v[156:157], v[156:157], v[196:197], v[222:223] op_sel:[0,0,0] op_sel_hi:[1,0,1]
	v_pk_fma_f32 v[226:227], v[156:157], v[216:217], v[226:227] op_sel:[0,0,0] op_sel_hi:[1,0,1]
	v_pk_mul_f32 v[224:225], v[220:221], v[208:209] op_sel:[0,1] op_sel_hi:[1,1]
	v_pk_fma_f32 v[158:159], v[158:159], v[196:197], v[224:225] op_sel:[0,1,0] op_sel_hi:[1,1,1]
	v_pk_fma_f32 v[228:229], v[158:159], v[216:217], v[228:229] op_sel:[0,1,0] op_sel_hi:[1,1,1]
	v_pk_mul_f32 v[222:223], v[220:221], v[210:211] op_sel:[0,0] op_sel_hi:[1,0]
	v_pk_fma_f32 v[160:161], v[160:161], v[198:199], v[222:223] op_sel:[0,0,0] op_sel_hi:[1,0,1]
	v_pk_fma_f32 v[226:227], v[160:161], v[218:219], v[226:227] op_sel:[0,0,0] op_sel_hi:[1,0,1]
	v_pk_mul_f32 v[224:225], v[220:221], v[210:211] op_sel:[0,1] op_sel_hi:[1,1]
	v_pk_fma_f32 v[162:163], v[162:163], v[198:199], v[224:225] op_sel:[0,1,0] op_sel_hi:[1,1,1]
	v_pk_fma_f32 v[228:229], v[162:163], v[218:219], v[228:229] op_sel:[0,1,0] op_sel_hi:[1,1,1]
	v_pk_add_f32 v[226:227], v[226:227], v[228:229]
	ds_write_b64 v235, v[226:227] offset:14336
	global_store_dwordx2 v207, v[100:101], s[38:39] nt
	global_store_dwordx2 v207, v[102:103], s[38:39] offset:512 nt
	global_store_dwordx2 v207, v[104:105], s[38:39] offset:1024 nt
	global_store_dwordx2 v207, v[106:107], s[38:39] offset:1536 nt
	global_store_dwordx2 v207, v[108:109], s[38:39] offset:2048 nt
	global_store_dwordx2 v207, v[110:111], s[38:39] offset:2560 nt
	global_store_dwordx2 v207, v[112:113], s[38:39] offset:3072 nt
	global_store_dwordx2 v207, v[114:115], s[38:39] offset:3584 nt
	s_add_u32 s38, s38, 0x1000
	s_addc_u32 s39, s39, 0
	global_store_dwordx2 v207, v[116:117], s[38:39] nt
	global_store_dwordx2 v207, v[118:119], s[38:39] offset:512 nt
	global_store_dwordx2 v207, v[120:121], s[38:39] offset:1024 nt
	global_store_dwordx2 v207, v[122:123], s[38:39] offset:1536 nt
	global_store_dwordx2 v207, v[124:125], s[38:39] offset:2048 nt
	global_store_dwordx2 v207, v[126:127], s[38:39] offset:2560 nt
	global_store_dwordx2 v207, v[128:129], s[38:39] offset:3072 nt
	global_store_dwordx2 v207, v[130:131], s[38:39] offset:3584 nt
	s_add_u32 s38, s38, 0x1000
	s_addc_u32 s39, s39, 0
	global_store_dwordx2 v207, v[132:133], s[38:39] nt
	global_store_dwordx2 v207, v[134:135], s[38:39] offset:512 nt
	global_store_dwordx2 v207, v[136:137], s[38:39] offset:1024 nt
	global_store_dwordx2 v207, v[138:139], s[38:39] offset:1536 nt
	global_store_dwordx2 v207, v[140:141], s[38:39] offset:2048 nt
	global_store_dwordx2 v207, v[142:143], s[38:39] offset:2560 nt
	global_store_dwordx2 v207, v[144:145], s[38:39] offset:3072 nt
	global_store_dwordx2 v207, v[146:147], s[38:39] offset:3584 nt
	s_add_u32 s38, s38, 0x1000
	s_addc_u32 s39, s39, 0
	global_store_dwordx2 v207, v[148:149], s[38:39] nt
	global_store_dwordx2 v207, v[150:151], s[38:39] offset:512 nt
	global_store_dwordx2 v207, v[152:153], s[38:39] offset:1024 nt
	global_store_dwordx2 v207, v[154:155], s[38:39] offset:1536 nt
	global_store_dwordx2 v207, v[156:157], s[38:39] offset:2048 nt
	global_store_dwordx2 v207, v[158:159], s[38:39] offset:2560 nt
	global_store_dwordx2 v207, v[160:161], s[38:39] offset:3072 nt
	global_store_dwordx2 v207, v[162:163], s[38:39] offset:3584 nt
	s_waitcnt lgkmcnt(0)
	s_barrier
; __device__ __forceinline__ bf16_t f2bf(float f) { return (bf16_t)(cvt_pk_bf16(f, 0.f) & 0xffffu); }
; __device__ __forceinline__ void hgrn_sample_pair(const Params& p, float* lds, int unit) {
;     ...
;     if (unit >= 0) { const int t = wq; const float* pp = po + (t * 2) * 128;
;         const float a = pp[lane] + pp[128 + lane], b = pp[lane + 64] + pp[128 + lane + 64];
;         const float rstd = rsqrtf(wave_sum(a * a + b * b) * (1.0f / DV) + EPS); const int row = rowbase + t; const size_t g = (size_t)row * 512 + h * 128;
;         CAT[(size_t)row * DM + h * 128 + lane] = f2bf(a * rstd * gn0 * gt0); CAT[(size_t)row * DM + h * 128 + lane + 64] = f2bf(b * rstd * gn1 * gt1); }
	ds_read_b32 v164, v236 offset:8192
	ds_read_b32 v165, v236 offset:8704
	ds_read_b32 v166, v236 offset:9216
	ds_read_b32 v167, v236 offset:9728
	ds_read_b32 v168, v236 offset:8448
	ds_read_b32 v169, v236 offset:8960
	ds_read_b32 v170, v236 offset:9472
	ds_read_b32 v171, v236 offset:9984
	v_readfirstlane_b32 s4, v0
	s_lshr_b32 s36, s4, 2
	s_and_b32 s4, s4, 3
	s_lshl_b32 s36, s36, 2
	s_addk_i32 s36, 0x4000
	s_add_u32 s36, s36, s5
	s_lshl_b32 s36, s36, 11
	s_lshl_b32 s4, s4, 8
	s_add_u32 s36, s36, s4
	s_add_u32 s20, s20, s36
	s_addc_u32 s21, s21, 0
	s_add_u32 s20, s20, 0x96f5e00
	s_addc_u32 s21, s21, 0
	s_waitcnt lgkmcnt(0)
	v_add_f32_e32 v164, v164, v165
	v_add_f32_e32 v166, v166, v167
	v_add_f32_e32 v168, v168, v169
	v_add_f32_e32 v170, v170, v171
	v_add_f32_e32 v164, v164, v166
	v_add_f32_e32 v168, v168, v170
	v_mul_f32_e32 v25, v164, v164
	v_fmac_f32_e32 v25, v168, v168
	s_nop 1
	v_add_f32_dpp v25, v25, v25 quad_perm:[1,0,3,2] row_mask:0xf bank_mask:0xf bound_ctrl:1
	s_nop 1
	v_add_f32_dpp v25, v25, v25 quad_perm:[2,3,0,1] row_mask:0xf bank_mask:0xf bound_ctrl:1
	s_nop 1
	v_add_f32_dpp v25, v25, v25 row_half_mirror row_mask:0xf bank_mask:0xf bound_ctrl:1
	s_nop 1
	v_add_f32_dpp v25, v25, v25 row_mirror row_mask:0xf bank_mask:0xf bound_ctrl:1
	s_nop 1
	v_readlane_b32 s36, v25, 0
	v_readlane_b32 s37, v25, 16
	v_readlane_b32 s40, v25, 32
	v_readlane_b32 s41, v25, 48
	v_mov_b32_e32 v26, s37
	v_mov_b32_e32 v27, s41
	v_add_f32_e32 v26, s36, v26
	v_add_f32_e32 v27, s40, v27
	v_add_f32_e32 v26, v26, v27
	v_mov_b32_e32 v27, 0x358637bd
	v_fmamk_f32 v26, v26, 0x3c000000, v27
	v_rsq_f32_e32 v26, v26
	s_nop 0
	v_mul_f32_e32 v164, v164, v26
	v_mul_f32_e32 v168, v168, v26
	v_mul_f32_e32 v164, v164, v21
	v_mul_f32_e32 v168, v168, v22
	v_mul_f32_e32 v164, v164, v23
	v_mul_f32_e32 v168, v168, v24
	v_cvt_pk_bf16_f32 v164, v164, v164
	v_cvt_pk_bf16_f32 v168, v168, v168
	global_store_short v238, v164, s[20:21]
	global_store_short v238, v168, s[20:21] offset:128
	s_branch .LBB0_326

; __global__ void __launch_bounds__(512, 2) hymba_fwd(Params p) {
;     ...
;         for (int u = bx; u < NB * HEADS * NSEG; u += G) { hgrn_seg<true>(p, lds, u >> 5, (u >> 3) & 3, u & 7);
;             const int seg = u & 7, ne = seg < 2 ? 2 : (seg < 6 ? 1 : 0), o0 = (int)((0x88765420u >> (4 * seg)) & 15u);
;             for (int k = 0; k < ne; ++k) conv_pair<16>(p, lds, false, 2 * ((u >> 3) * 8 + o0 + k) + (threadIdx.x >> 8)); }
.LBB0_482:
	s_cmp_lt_u32 s49, 6
	s_cselect_b64 s[46:47], -1, 0
	v_cndmask_b32_e64 v0, 0, 1, s[46:47]
	s_waitcnt lgkmcnt(0)
	s_barrier
	s_cmp_gt_u32 s49, 2
	v_readfirstlane_b32 s4, v0
	s_cselect_b32 s4, s4, 2
	v_readlane_b32 s64, v247, 38
	v_readlane_b32 s52, v247, 36
	s_cmp_eq_u32 s4, 0
	v_readlane_b32 s65, v247, 39
	v_readlane_b32 s66, v247, 40
	v_readlane_b32 s67, v247, 41
	v_readlane_b32 s53, v247, 37
	s_cbranch_scc1 .LBB0_461
	s_lshl_b32 s46, s48, 4
	s_lshl_b32 s47, s48, 8
	s_cmp_eq_u32 s49, 5
	s_cbranch_scc1 .Lp2b_seg6
	s_lshl_b32 s48, s49, 2
	s_lshr_b32 s48, 0x88876420, s48
	s_and_b32 s49, s48, 15
	s_lshl_b32 s48, s4, 5
	s_lshl_b32 s4, s49, 1
	s_add_i32 s4, s4, s46
	v_add_u32_e32 v136, s4, v96
	s_lshl_b32 s4, s49, 5
	s_add_i32 s4, s4, s47
	v_add_u32_e32 v137, s4, v130
	s_mov_b32 s49, 0
	s_branch .LBB0_485
